# GEMM K loops shifted by 4 bytes (dead s_nop) so the 32-MFMA runs start on 8-byte boundaries again
# baseline (speedup 1.0000x reference)
; #define PG8_STAGE(bufoff, gbase, voff) do { _Pragma("unroll") for (int _i = 0; _i < 2; ++_i) \
;         __builtin_amdgcn_global_load_lds((const unsigned*)((const char*)(gbase) + (voff)[_i]), (LAS unsigned*)(lds + (bufoff) + ldsw + _i * 8192), 16, 0, 0); } while (0)
; #define PG8_LDA(dst, b, h) do { _Pragma("unroll") for (int m = 0; m < 4; ++m) _Pragma("unroll") for (int k = 0; k < 2; ++k) dst[m][k] = *(const LAS bf16x8*)(lds + PG8_SA(b, h) + aoff + m * 2048 + k * 1024); } while (0)
; #define PG8_LDB(dst, b, h) do { _Pragma("unroll") for (int n = 0; n < 2; ++n) _Pragma("unroll") for (int k = 0; k < 2; ++k) dst[n][k] = *(const LAS bf16x8*)(lds + PG8_SB(b, h) + boff + n * 2048 + k * 1024); } while (0)
; #define PG8_SCHED __builtin_amdgcn_sched_barrier(0)
;     __device__ __forceinline__ void rescale(f32x4 (&acc)[2][2][4][2], const Unit& u, int which, int wr, int wc, int fr, int fq) const { EpiBranchCat e; e.gates = (const bf16_t*)d.q0; e.mb = nullptr; e.rescale(acc, u, which, wr, wc, fr, fq); }
; template <class Epi>
; __device__ __forceinline__ void gemm_phase(LAS unsigned char* lds, const Gemm g, const StaticOrder& S, const Epi& E, const bool perm) {
;     ...
;     for (;;) {
;         const bool has_next = S.next(ui + 1, nxt);
;         const char* nA = has_next ? (const char*)g.A + (size_t)nxt.pm * tstep : cA; const char* nB = has_next ? (const char*)g.Bt + (size_t)nxt.pn * tstep : cB;
;         for (int t = 0; t < nt; t += 2) {
;             if (E.hook() && (t == 8 || t == 16)) E.rescale(acc, cur, t >> 4, wr, wc, fr, fq);
;             const bool last = (t == nt - 2);
;             const char* a1 = cA + (size_t)(t + 1) * kstep;
;             const char* a2 = last ? nA : cA + (size_t)(t + 2) * kstep; const char* b2 = last ? nB : cB + (size_t)(t + 2) * kstep;
;             const char* a3 = a2 + kstep; const char* b3 = b2 + kstep;
;             PG8_LDB(B0, 0, 0); PG8_SCHED; PG8_LDA(At, 0, 0); PG8_STAGE(PG8_SA(1, 1), a1 + hstep, voffA);
.LBB0_461:
	s_lshl_b32 s51, s70, 8
	s_add_u32 s6, s6, 0x80
	s_addc_u32 s7, s7, 0
	s_add_u32 s55, s22, 0x100
	v_lshl_add_u32 v218, s46, 8, v244
	v_or_b32_e32 v220, s51, v246
	s_addc_u32 s78, s23, 0
	s_mov_b32 s79, 0
	s_mov_b32 s60, 0
	s_branch .LBB0_463
	s_nop 0
